# v18 + attention out-projection (EpiResid) epilogue: second row-half residual loads issued right behind the first half's into free registers, flat->global, counted waits (no wait behind the first half'
# baseline (speedup 1.0000x reference)
; __device__ __forceinline__ u32x4 pack8(f32x4 a, f32x4 b) { u32x4 w; w.x = cvt_pk_bf16(a[0], a[1]); w.y = cvt_pk_bf16(a[2], a[3]); w.z = cvt_pk_bf16(b[0], b[1]); w.w = cvt_pk_bf16(b[2], b[3]); return w; }
; __device__ __forceinline__ float bf_lo(unsigned w) { return __uint_as_float(w << 16); }
; __device__ __forceinline__ float bf_hi(unsigned w) { return __uint_as_float(w & 0xffff0000u); }
; __device__ __forceinline__ float hsum4(f32x4 v) { return (v[0] + v[1]) + (v[2] + v[3]); }
; __device__ __forceinline__ float hsq4(f32x4 v) { return (v[0] * v[0] + v[1] * v[1]) + (v[2] * v[2] + v[3] * v[3]); }
; __device__ __forceinline__ float fq_sum(float s) { return x16x32_sum(s); }
;     __device__ __forceinline__ void operator()(EP_ARGS) const {
;     ...
;             if (!xf) {
; #pragma unroll
;                 for (int m = 0; m < 4; ++m)
; #pragma unroll
;                     for (int bj = 0; bj < 2; ++bj) rw[m][bj] = *(const u32x4*)(xh + (size_t)EP_ROW(ai, m) * DM + EP_COL8(bj));
;                 __builtin_amdgcn_sched_barrier(0); }
; #pragma unroll
;             for (int m = 0; m < 4; ++m) { const int row = EP_ROW(ai, m); float s = 0.f, q = 0.f;
; #pragma unroll
;                 for (int bj = 0; bj < 2; ++bj) { const size_t o = (size_t)row * DM + EP_COL8(bj);
;                     f32x4 r0, r1; if (xf) { r0 = *(const f32x4*)(xf + o); r1 = *(const f32x4*)(xf + o + 4); }
;                     else { const u32x4 w = rw[m][bj]; r0 = (f32x4){bf_lo(w.x), bf_hi(w.x), bf_lo(w.y), bf_hi(w.y)}; r1 = (f32x4){bf_lo(w.z), bf_hi(w.z), bf_lo(w.w), bf_hi(w.w)}; }
;                     const f32x4 y0 = r0 * ALPHA + acc[ai][bj][m][0], y1 = r1 * ALPHA + acc[ai][bj][m][1];
;                     *(u32x4*)(Yh + o) = pack8(y0, y1);
;                     s += hsum4(y0) + hsum4(y1); q += hsq4(y0) + hsq4(y1); }
;                 s = fq_sum(s); q = fq_sum(q);
;                 if (fq == 0) atomic_add_stat(stats + (size_t)row, s, q); }
.LBB0_1107:
	v_lshl_add_u32 v156, s54, 8, v170
	v_lshl_or_b32 v152, s52, 8, v173
	v_ashrrev_i32_e32 v157, 31, v156
	v_ashrrev_i32_e32 v153, 31, v152
	v_lshlrev_b64 v[182:183], 12, v[156:157]
	v_lshl_add_u64 v[128:129], s[4:5], 0, v[182:183]
	v_lshlrev_b64 v[154:155], 1, v[152:153]
	v_lshl_add_u64 v[128:129], v[128:129], 0, v[154:155]
	global_load_dwordx4 v[174:177], v[128:129], off
	global_load_dwordx4 v[178:181], v[128:129], off offset:256
	v_or_b32_e32 v128, 16, v156
	v_ashrrev_i32_e32 v129, 31, v128
	v_lshlrev_b64 v[162:163], 12, v[128:129]
	v_lshl_add_u64 v[128:129], s[4:5], 0, v[162:163]
	v_lshl_add_u64 v[128:129], v[128:129], 0, v[154:155]
	global_load_dwordx4 v[148:151], v[128:129], off
	global_load_dwordx4 v[144:147], v[128:129], off offset:256
	v_or_b32_e32 v128, 32, v156
	v_ashrrev_i32_e32 v129, 31, v128
	v_lshlrev_b64 v[160:161], 12, v[128:129]
	v_lshl_add_u64 v[128:129], s[4:5], 0, v[160:161]
	v_lshl_add_u64 v[128:129], v[128:129], 0, v[154:155]
	global_load_dwordx4 v[140:143], v[128:129], off
	global_load_dwordx4 v[136:139], v[128:129], off offset:256
	v_or_b32_e32 v128, 48, v156
	v_ashrrev_i32_e32 v129, 31, v128
	v_lshlrev_b64 v[158:159], 12, v[128:129]
	v_lshl_add_u64 v[128:129], s[4:5], 0, v[158:159]
	v_lshl_add_u64 v[128:129], v[128:129], 0, v[154:155]
	global_load_dwordx4 v[132:135], v[128:129], off
	s_nop 0
	global_load_dwordx4 v[128:131], v[128:129], off offset:256
	v_add_u32_e32 v210, 0x80, v156
	v_ashrrev_i32_e32 v211, 31, v210
	v_lshlrev_b64 v[244:245], 12, v[210:211]
	v_lshl_add_u64 v[210:211], s[4:5], 0, v[244:245]
	v_lshl_add_u64 v[210:211], v[210:211], 0, v[154:155]
	global_load_dwordx4 v[194:197], v[210:211], off
	v_add_u32_e32 v210, 0x80, v156
	v_ashrrev_i32_e32 v211, 31, v210
	v_lshlrev_b64 v[244:245], 12, v[210:211]
	v_lshl_add_u64 v[210:211], s[4:5], 0, v[244:245]
	v_lshl_add_u64 v[210:211], v[210:211], 0, v[154:155]
	global_load_dwordx4 v[198:201], v[210:211], off offset:256
	v_add_u32_e32 v210, 0x90, v156
	v_ashrrev_i32_e32 v211, 31, v210
	v_lshlrev_b64 v[244:245], 12, v[210:211]
	v_lshl_add_u64 v[210:211], s[4:5], 0, v[244:245]
	v_lshl_add_u64 v[210:211], v[210:211], 0, v[154:155]
	global_load_dwordx4 v[202:205], v[210:211], off
	v_add_u32_e32 v210, 0x90, v156
	v_ashrrev_i32_e32 v211, 31, v210
	v_lshlrev_b64 v[244:245], 12, v[210:211]
	v_lshl_add_u64 v[210:211], s[4:5], 0, v[244:245]
	v_lshl_add_u64 v[210:211], v[210:211], 0, v[154:155]
	global_load_dwordx4 v[206:209], v[210:211], off offset:256
	v_add_u32_e32 v210, 0xa0, v156
	v_ashrrev_i32_e32 v211, 31, v210
	v_lshlrev_b64 v[244:245], 12, v[210:211]
	v_lshl_add_u64 v[210:211], s[4:5], 0, v[244:245]
	v_lshl_add_u64 v[210:211], v[210:211], 0, v[154:155]
	global_load_dwordx4 v[214:217], v[210:211], off
	v_add_u32_e32 v210, 0xa0, v156
	v_ashrrev_i32_e32 v211, 31, v210
	v_lshlrev_b64 v[244:245], 12, v[210:211]
	v_lshl_add_u64 v[210:211], s[4:5], 0, v[244:245]
	v_lshl_add_u64 v[210:211], v[210:211], 0, v[154:155]
	global_load_dwordx4 v[232:235], v[210:211], off offset:256
	v_add_u32_e32 v210, 0xb0, v156
	v_ashrrev_i32_e32 v211, 31, v210
	v_lshlrev_b64 v[244:245], 12, v[210:211]
	v_lshl_add_u64 v[210:211], s[4:5], 0, v[244:245]
	v_lshl_add_u64 v[210:211], v[210:211], 0, v[154:155]
	global_load_dwordx4 v[236:239], v[210:211], off
	v_add_u32_e32 v210, 0xb0, v156
	v_ashrrev_i32_e32 v211, 31, v210
	v_lshlrev_b64 v[244:245], 12, v[210:211]
	v_lshl_add_u64 v[210:211], s[4:5], 0, v[244:245]
	v_lshl_add_u64 v[210:211], v[210:211], 0, v[154:155]
	global_load_dwordx4 v[240:243], v[210:211], off offset:256
	s_waitcnt vmcnt(8)
	v_lshlrev_b32_e32 v190, 16, v174
	v_and_b32_e32 v191, 0xffff0000, v174
	v_lshlrev_b32_e32 v174, 16, v175
	v_and_b32_e32 v175, 0xffff0000, v175
	v_lshlrev_b32_e32 v192, 16, v176
	v_and_b32_e32 v193, 0xffff0000, v176
	v_lshlrev_b32_e32 v176, 16, v177
	v_and_b32_e32 v177, 0xffff0000, v177
	v_lshl_add_u64 v[182:183], s[6:7], 0, v[182:183]
	v_pk_fma_f32 v[126:127], v[174:175], s[28:29], v[126:127] op_sel_hi:[1,0,1]
	v_pk_fma_f32 v[124:125], v[190:191], s[28:29], v[124:125] op_sel_hi:[1,0,1]
	v_pk_fma_f32 v[174:175], v[176:177], s[28:29], v[122:123] op_sel_hi:[1,0,1]
	v_pk_fma_f32 v[176:177], v[192:193], s[28:29], v[120:121] op_sel_hi:[1,0,1]
	v_cvt_pk_bf16_f32 v120, v124, v125
	v_cvt_pk_bf16_f32 v121, v126, v127
	v_lshl_add_u64 v[182:183], v[182:183], 0, v[154:155]
	v_cvt_pk_bf16_f32 v122, v176, v177
	v_cvt_pk_bf16_f32 v123, v174, v175
	global_store_dwordx4 v[182:183], v[120:123], off
	s_nop 1
	v_add_f32_e32 v120, v124, v125
	v_add_f32_e32 v121, v126, v127
	v_add_f32_e32 v120, v120, v121
	v_add_f32_e32 v121, v176, v177
	v_add_f32_e32 v122, v174, v175
	v_add_f32_e32 v121, v121, v122
	v_add_f32_e32 v120, v120, v121
	v_add_f32_e32 v184, 0, v120
	v_mul_f32_e32 v120, v125, v125
	v_mul_f32_e32 v121, v127, v127
	v_fmac_f32_e32 v120, v124, v124
	v_fmac_f32_e32 v121, v126, v126
	v_add_f32_e32 v120, v120, v121
	v_mul_f32_e32 v121, v177, v177
	v_mul_f32_e32 v122, v175, v175
	v_fmac_f32_e32 v121, v176, v176
	v_fmac_f32_e32 v122, v174, v174
	v_add_f32_e32 v121, v121, v122
	v_add_f32_e32 v174, v120, v121
	v_lshlrev_b32_e32 v120, 16, v178
	v_and_b32_e32 v121, 0xffff0000, v178
	v_lshlrev_b32_e32 v122, 16, v179
	v_and_b32_e32 v123, 0xffff0000, v179
	v_lshlrev_b32_e32 v124, 16, v180
	v_and_b32_e32 v125, 0xffff0000, v180
	v_lshlrev_b32_e32 v126, 16, v181
	v_and_b32_e32 v127, 0xffff0000, v181
	v_pk_fma_f32 v[118:119], v[122:123], s[28:29], v[118:119] op_sel_hi:[1,0,1]
	v_pk_fma_f32 v[116:117], v[120:121], s[28:29], v[116:117] op_sel_hi:[1,0,1]
	v_pk_fma_f32 v[122:123], v[124:125], s[28:29], v[112:113] op_sel_hi:[1,0,1]
	v_cvt_pk_bf16_f32 v112, v116, v117
	v_cvt_pk_bf16_f32 v113, v118, v119
	v_pk_fma_f32 v[120:121], v[126:127], s[28:29], v[114:115] op_sel_hi:[1,0,1]
	v_cvt_pk_bf16_f32 v114, v122, v123
	s_nop 0
	v_cvt_pk_bf16_f32 v115, v120, v121
	global_store_dwordx4 v[182:183], v[112:115], off offset:256
	s_nop 1
	v_add_f32_e32 v112, v116, v117
	v_add_f32_e32 v113, v118, v119
	v_add_f32_e32 v112, v112, v113
	v_add_f32_e32 v113, v122, v123
	v_add_f32_e32 v114, v120, v121
	v_add_f32_e32 v113, v113, v114
	v_add_f32_e32 v112, v112, v113
	v_mul_f32_e32 v113, v117, v117
	v_mul_f32_e32 v114, v119, v119
	v_fmac_f32_e32 v113, v116, v116
	v_fmac_f32_e32 v114, v118, v118
	v_add_f32_e32 v113, v113, v114
	v_mul_f32_e32 v114, v123, v123
	v_mul_f32_e32 v115, v121, v121
	v_fmac_f32_e32 v114, v122, v122
	v_fmac_f32_e32 v115, v120, v120
	v_add_f32_e32 v112, v184, v112
	v_add_f32_e32 v114, v114, v115
	v_add_f32_e32 v113, v113, v114
	v_mov_b32_e32 v114, v112
	v_add_f32_e32 v113, v174, v113
	s_nop 0
	v_permlane16_swap_b32_e32 v112, v114
	v_add_f32_e32 v114, v112, v114
	v_mov_b32_e32 v112, v113
	s_nop 1
	v_permlane16_swap_b32_e32 v113, v112
	v_add_f32_e32 v116, v113, v112
	v_mov_b32_e32 v115, v114
	v_mov_b32_e32 v117, v116
	s_nop 0
	v_permlane32_swap_b32_e32 v114, v115
	v_permlane32_swap_b32_e32 v116, v117
	v_lshl_add_u64 v[112:113], v[156:157], 3, s[8:9]
	s_and_saveexec_b64 s[12:13], s[42:43]
	s_cbranch_execz .LBB0_1109
; __device__ __forceinline__ u32x4 pack8(f32x4 a, f32x4 b) { u32x4 w; w.x = cvt_pk_bf16(a[0], a[1]); w.y = cvt_pk_bf16(a[2], a[3]); w.z = cvt_pk_bf16(b[0], b[1]); w.w = cvt_pk_bf16(b[2], b[3]); return w; }
; __device__ __forceinline__ float bf_lo(unsigned w) { return __uint_as_float(w << 16); }
; __device__ __forceinline__ float bf_hi(unsigned w) { return __uint_as_float(w & 0xffff0000u); }
; __device__ __forceinline__ float hsum4(f32x4 v) { return (v[0] + v[1]) + (v[2] + v[3]); }
; __device__ __forceinline__ float hsq4(f32x4 v) { return (v[0] * v[0] + v[1] * v[1]) + (v[2] * v[2] + v[3] * v[3]); }
; __device__ __forceinline__ float fq_sum(float s) { return x16x32_sum(s); }
;     __device__ __forceinline__ void operator()(EP_ARGS) const {
;     ...
;             for (int m = 0; m < 4; ++m) { const int row = EP_ROW(ai, m); float s = 0.f, q = 0.f;
; #pragma unroll
;                 for (int bj = 0; bj < 2; ++bj) { const size_t o = (size_t)row * DM + EP_COL8(bj);
;                     f32x4 r0, r1; if (xf) { r0 = *(const f32x4*)(xf + o); r1 = *(const f32x4*)(xf + o + 4); }
;                     else { const u32x4 w = rw[m][bj]; r0 = (f32x4){bf_lo(w.x), bf_hi(w.x), bf_lo(w.y), bf_hi(w.y)}; r1 = (f32x4){bf_lo(w.z), bf_hi(w.z), bf_lo(w.w), bf_hi(w.w)}; }
;                     const f32x4 y0 = r0 * ALPHA + acc[ai][bj][m][0], y1 = r1 * ALPHA + acc[ai][bj][m][1];
;                     *(u32x4*)(Yh + o) = pack8(y0, y1);
;                     s += hsum4(y0) + hsum4(y1); q += hsq4(y0) + hsq4(y1); }
;                 s = fq_sum(s); q = fq_sum(q);
;                 if (fq == 0) atomic_add_stat(stats + (size_t)row, s, q); }
	v_add_f32_e32 v114, v114, v115
	v_mul_f32_e32 v114, 0x46800000, v114
	v_add_f32_e32 v116, v116, v117
	v_rndne_f32_e32 v114, v114
	v_cvt_i32_f32_e32 v115, v114
	v_mul_f32_e32 v114, 0x44800000, v116
	v_rndne_f32_e32 v114, v114
	v_cvt_u32_f32_e32 v114, v114
	global_atomic_add_x2 v[112:113], v[114:115], off
.LBB0_1109:
	s_or_b64 exec, exec, s[12:13]
	v_lshlrev_b32_e32 v116, 16, v149
	v_and_b32_e32 v117, 0xffff0000, v149
	v_lshlrev_b32_e32 v118, 16, v150
	v_and_b32_e32 v119, 0xffff0000, v150
	v_lshlrev_b32_e32 v114, 16, v148
	v_and_b32_e32 v115, 0xffff0000, v148
	v_pk_fma_f32 v[110:111], v[116:117], s[28:29], v[110:111] op_sel_hi:[1,0,1]
	v_pk_fma_f32 v[116:117], v[118:119], s[28:29], v[104:105] op_sel_hi:[1,0,1]
	v_lshl_add_u64 v[118:119], s[6:7], 0, v[162:163]
	v_lshlrev_b32_e32 v120, 16, v151
	v_and_b32_e32 v121, 0xffff0000, v151
	v_pk_fma_f32 v[108:109], v[114:115], s[28:29], v[108:109] op_sel_hi:[1,0,1]
	v_lshl_add_u64 v[118:119], v[152:153], 1, v[118:119]
	v_cvt_pk_bf16_f32 v104, v108, v109
	v_cvt_pk_bf16_f32 v105, v110, v111
	v_pk_fma_f32 v[114:115], v[120:121], s[28:29], v[106:107] op_sel_hi:[1,0,1]
	v_cvt_pk_bf16_f32 v106, v116, v117
	s_nop 0
	v_cvt_pk_bf16_f32 v107, v114, v115
	global_store_dwordx4 v[118:119], v[104:107], off
	s_nop 1
	v_add_f32_e32 v104, v108, v109
	v_add_f32_e32 v105, v110, v111
	v_add_f32_e32 v104, v104, v105
	v_add_f32_e32 v105, v116, v117
	v_add_f32_e32 v106, v114, v115
	v_add_f32_e32 v105, v105, v106
	v_add_f32_e32 v104, v104, v105
	v_add_f32_e32 v120, 0, v104
	v_mul_f32_e32 v104, v109, v109
	v_mul_f32_e32 v105, v111, v111
	v_fmac_f32_e32 v104, v108, v108
	v_fmac_f32_e32 v105, v110, v110
	v_add_f32_e32 v104, v104, v105
	v_mul_f32_e32 v105, v117, v117
	v_mul_f32_e32 v106, v115, v115
	v_fmac_f32_e32 v105, v116, v116
	v_fmac_f32_e32 v106, v114, v114
	v_add_f32_e32 v105, v105, v106
	v_add_f32_e32 v114, v104, v105
	v_lshlrev_b32_e32 v104, 16, v144
	v_and_b32_e32 v105, 0xffff0000, v144
	v_lshlrev_b32_e32 v106, 16, v145
	v_and_b32_e32 v107, 0xffff0000, v145
	v_lshlrev_b32_e32 v108, 16, v146
	v_and_b32_e32 v109, 0xffff0000, v146
	v_lshlrev_b32_e32 v110, 16, v147
	v_and_b32_e32 v111, 0xffff0000, v147
	v_pk_fma_f32 v[102:103], v[106:107], s[28:29], v[102:103] op_sel_hi:[1,0,1]
	v_pk_fma_f32 v[100:101], v[104:105], s[28:29], v[100:101] op_sel_hi:[1,0,1]
	v_pk_fma_f32 v[106:107], v[108:109], s[28:29], v[96:97] op_sel_hi:[1,0,1]
	v_cvt_pk_bf16_f32 v96, v100, v101
	v_cvt_pk_bf16_f32 v97, v102, v103
	v_pk_fma_f32 v[104:105], v[110:111], s[28:29], v[98:99] op_sel_hi:[1,0,1]
	v_cvt_pk_bf16_f32 v98, v106, v107
	s_nop 0
	v_cvt_pk_bf16_f32 v99, v104, v105
	global_store_dwordx4 v[118:119], v[96:99], off offset:256
	s_nop 1
	v_add_f32_e32 v96, v100, v101
	v_add_f32_e32 v97, v102, v103
	v_add_f32_e32 v96, v96, v97
	v_add_f32_e32 v97, v106, v107
	v_add_f32_e32 v98, v104, v105
	v_add_f32_e32 v97, v97, v98
	v_add_f32_e32 v96, v96, v97
	v_mul_f32_e32 v97, v101, v101
	v_mul_f32_e32 v98, v103, v103
	v_fmac_f32_e32 v97, v100, v100
	v_fmac_f32_e32 v98, v102, v102
	v_add_f32_e32 v97, v97, v98
	v_mul_f32_e32 v98, v107, v107
	v_mul_f32_e32 v99, v105, v105
	v_fmac_f32_e32 v98, v106, v106
	v_fmac_f32_e32 v99, v104, v104
	v_add_f32_e32 v98, v98, v99
	v_add_f32_e32 v97, v97, v98
	v_add_f32_e32 v96, v120, v96
	v_add_f32_e32 v98, v114, v97
	v_mov_b32_e32 v97, v96
	v_mov_b32_e32 v99, v98
	s_nop 0
	v_permlane16_swap_b32_e32 v96, v97
	v_permlane16_swap_b32_e32 v98, v99
	v_add_f32_e32 v96, v96, v97
	v_add_f32_e32 v98, v98, v99
	v_mov_b32_e32 v97, v96
	v_mov_b32_e32 v99, v98
	s_nop 0
	v_permlane32_swap_b32_e32 v96, v97
	v_permlane32_swap_b32_e32 v98, v99
	s_and_saveexec_b64 s[12:13], s[42:43]
	s_cbranch_execz .LBB0_1111
	v_add_f32_e32 v96, v96, v97
	v_mul_f32_e32 v96, 0x46800000, v96
	v_add_f32_e32 v98, v98, v99
	v_rndne_f32_e32 v96, v96
	v_cvt_i32_f32_e32 v97, v96
	v_mul_f32_e32 v96, 0x44800000, v98
	v_rndne_f32_e32 v96, v96
	v_cvt_u32_f32_e32 v96, v96
	global_atomic_add_x2 v[112:113], v[96:97], off offset:128
.LBB0_1111:
	s_or_b64 exec, exec, s[12:13]
	v_lshlrev_b32_e32 v98, 16, v141
	v_and_b32_e32 v99, 0xffff0000, v141
	v_lshlrev_b32_e32 v100, 16, v142
	v_and_b32_e32 v101, 0xffff0000, v142
	v_lshlrev_b32_e32 v96, 16, v140
	v_and_b32_e32 v97, 0xffff0000, v140
	v_pk_fma_f32 v[94:95], v[98:99], s[28:29], v[94:95] op_sel_hi:[1,0,1]
	v_pk_fma_f32 v[98:99], v[100:101], s[28:29], v[88:89] op_sel_hi:[1,0,1]
	v_lshl_add_u64 v[100:101], s[6:7], 0, v[160:161]
	v_lshlrev_b32_e32 v102, 16, v143
	v_and_b32_e32 v103, 0xffff0000, v143
	v_pk_fma_f32 v[92:93], v[96:97], s[28:29], v[92:93] op_sel_hi:[1,0,1]
	v_lshl_add_u64 v[100:101], v[152:153], 1, v[100:101]
	v_cvt_pk_bf16_f32 v88, v92, v93
	v_cvt_pk_bf16_f32 v89, v94, v95
	v_pk_fma_f32 v[96:97], v[102:103], s[28:29], v[90:91] op_sel_hi:[1,0,1]
	v_cvt_pk_bf16_f32 v90, v98, v99
	s_nop 0
	v_cvt_pk_bf16_f32 v91, v96, v97
	global_store_dwordx4 v[100:101], v[88:91], off
	s_nop 1
	v_add_f32_e32 v88, v92, v93
	v_add_f32_e32 v89, v94, v95
	v_add_f32_e32 v88, v88, v89
	v_add_f32_e32 v89, v98, v99
	v_add_f32_e32 v90, v96, v97
	v_add_f32_e32 v89, v89, v90
	v_add_f32_e32 v88, v88, v89
	v_add_f32_e32 v102, 0, v88
	v_mul_f32_e32 v88, v93, v93
	v_mul_f32_e32 v89, v95, v95
	v_fmac_f32_e32 v88, v92, v92
	v_fmac_f32_e32 v89, v94, v94
	v_add_f32_e32 v88, v88, v89
	v_mul_f32_e32 v89, v99, v99
	v_mul_f32_e32 v90, v97, v97
	v_fmac_f32_e32 v89, v98, v98
	v_fmac_f32_e32 v90, v96, v96
	v_add_f32_e32 v89, v89, v90
	v_add_f32_e32 v96, v88, v89
	v_lshlrev_b32_e32 v88, 16, v136
	v_and_b32_e32 v89, 0xffff0000, v136
	v_lshlrev_b32_e32 v90, 16, v137
	v_and_b32_e32 v91, 0xffff0000, v137
	v_lshlrev_b32_e32 v92, 16, v138
	v_and_b32_e32 v93, 0xffff0000, v138
; __device__ __forceinline__ u32x4 pack8(f32x4 a, f32x4 b) { u32x4 w; w.x = cvt_pk_bf16(a[0], a[1]); w.y = cvt_pk_bf16(a[2], a[3]); w.z = cvt_pk_bf16(b[0], b[1]); w.w = cvt_pk_bf16(b[2], b[3]); return w; }
; __device__ __forceinline__ float bf_lo(unsigned w) { return __uint_as_float(w << 16); }
; __device__ __forceinline__ float bf_hi(unsigned w) { return __uint_as_float(w & 0xffff0000u); }
; __device__ __forceinline__ float hsum4(f32x4 v) { return (v[0] + v[1]) + (v[2] + v[3]); }
; __device__ __forceinline__ float hsq4(f32x4 v) { return (v[0] * v[0] + v[1] * v[1]) + (v[2] * v[2] + v[3] * v[3]); }
; __device__ __forceinline__ float fq_sum(float s) { return x16x32_sum(s); }
;     __device__ __forceinline__ void operator()(EP_ARGS) const {
;     ...
;             for (int m = 0; m < 4; ++m) { const int row = EP_ROW(ai, m); float s = 0.f, q = 0.f;
; #pragma unroll
;                 for (int bj = 0; bj < 2; ++bj) { const size_t o = (size_t)row * DM + EP_COL8(bj);
;                     f32x4 r0, r1; if (xf) { r0 = *(const f32x4*)(xf + o); r1 = *(const f32x4*)(xf + o + 4); }
;                     else { const u32x4 w = rw[m][bj]; r0 = (f32x4){bf_lo(w.x), bf_hi(w.x), bf_lo(w.y), bf_hi(w.y)}; r1 = (f32x4){bf_lo(w.z), bf_hi(w.z), bf_lo(w.w), bf_hi(w.w)}; }
;                     const f32x4 y0 = r0 * ALPHA + acc[ai][bj][m][0], y1 = r1 * ALPHA + acc[ai][bj][m][1];
;                     *(u32x4*)(Yh + o) = pack8(y0, y1);
;                     s += hsum4(y0) + hsum4(y1); q += hsq4(y0) + hsq4(y1); }
;                 s = fq_sum(s); q = fq_sum(q);
;                 if (fq == 0) atomic_add_stat(stats + (size_t)row, s, q); }
	v_lshlrev_b32_e32 v94, 16, v139
	v_and_b32_e32 v95, 0xffff0000, v139
	v_pk_fma_f32 v[86:87], v[90:91], s[28:29], v[86:87] op_sel_hi:[1,0,1]
	v_pk_fma_f32 v[84:85], v[88:89], s[28:29], v[84:85] op_sel_hi:[1,0,1]
	v_pk_fma_f32 v[90:91], v[92:93], s[28:29], v[80:81] op_sel_hi:[1,0,1]
	v_cvt_pk_bf16_f32 v80, v84, v85
	v_cvt_pk_bf16_f32 v81, v86, v87
	v_pk_fma_f32 v[88:89], v[94:95], s[28:29], v[82:83] op_sel_hi:[1,0,1]
	v_cvt_pk_bf16_f32 v82, v90, v91
	s_nop 0
	v_cvt_pk_bf16_f32 v83, v88, v89
	global_store_dwordx4 v[100:101], v[80:83], off offset:256
	s_nop 1
	v_add_f32_e32 v80, v84, v85
	v_add_f32_e32 v81, v86, v87
	v_add_f32_e32 v80, v80, v81
	v_add_f32_e32 v81, v90, v91
	v_add_f32_e32 v82, v88, v89
	v_add_f32_e32 v81, v81, v82
	v_add_f32_e32 v80, v80, v81
	v_mul_f32_e32 v81, v85, v85
	v_mul_f32_e32 v82, v87, v87
	v_fmac_f32_e32 v81, v84, v84
	v_fmac_f32_e32 v82, v86, v86
	v_add_f32_e32 v81, v81, v82
	v_mul_f32_e32 v82, v91, v91
	v_mul_f32_e32 v83, v89, v89
	v_fmac_f32_e32 v82, v90, v90
	v_fmac_f32_e32 v83, v88, v88
	v_add_f32_e32 v82, v82, v83
	v_add_f32_e32 v81, v81, v82
	v_add_f32_e32 v80, v102, v80
	v_add_f32_e32 v82, v96, v81
	v_mov_b32_e32 v81, v80
	v_mov_b32_e32 v83, v82
	s_nop 0
	v_permlane16_swap_b32_e32 v80, v81
	v_permlane16_swap_b32_e32 v82, v83
	v_add_f32_e32 v80, v80, v81
	v_add_f32_e32 v82, v82, v83
	v_mov_b32_e32 v81, v80
	v_mov_b32_e32 v83, v82
	s_nop 0
	v_permlane32_swap_b32_e32 v80, v81
	v_permlane32_swap_b32_e32 v82, v83
	s_and_saveexec_b64 s[12:13], s[42:43]
	v_readlane_b32 s61, v255, 16
	v_readlane_b32 s59, v255, 18
	v_readlane_b32 s60, v255, 19
	s_cbranch_execz .LBB0_1113
	v_add_f32_e32 v80, v80, v81
	v_mul_f32_e32 v80, 0x46800000, v80
	v_add_f32_e32 v82, v82, v83
	v_rndne_f32_e32 v80, v80
	v_cvt_i32_f32_e32 v81, v80
	v_mul_f32_e32 v80, 0x44800000, v82
	v_rndne_f32_e32 v80, v80
	v_cvt_u32_f32_e32 v80, v80
	global_atomic_add_x2 v[112:113], v[80:81], off offset:256
.LBB0_1113:
	s_or_b64 exec, exec, s[12:13]
	v_lshlrev_b32_e32 v82, 16, v133
	v_and_b32_e32 v83, 0xffff0000, v133
	v_lshlrev_b32_e32 v84, 16, v134
	v_and_b32_e32 v85, 0xffff0000, v134
	v_lshlrev_b32_e32 v80, 16, v132
	v_and_b32_e32 v81, 0xffff0000, v132
	v_pk_fma_f32 v[78:79], v[82:83], s[28:29], v[78:79] op_sel_hi:[1,0,1]
	v_pk_fma_f32 v[82:83], v[84:85], s[28:29], v[72:73] op_sel_hi:[1,0,1]
	v_lshl_add_u64 v[84:85], s[6:7], 0, v[158:159]
	v_lshlrev_b32_e32 v86, 16, v135
	v_and_b32_e32 v87, 0xffff0000, v135
	v_pk_fma_f32 v[76:77], v[80:81], s[28:29], v[76:77] op_sel_hi:[1,0,1]
	v_lshl_add_u64 v[84:85], v[152:153], 1, v[84:85]
	v_cvt_pk_bf16_f32 v72, v76, v77
	v_cvt_pk_bf16_f32 v73, v78, v79
	v_pk_fma_f32 v[80:81], v[86:87], s[28:29], v[74:75] op_sel_hi:[1,0,1]
	v_cvt_pk_bf16_f32 v74, v82, v83
	s_nop 0
	v_cvt_pk_bf16_f32 v75, v80, v81
	global_store_dwordx4 v[84:85], v[72:75], off
	s_nop 1
	v_add_f32_e32 v72, v76, v77
	v_add_f32_e32 v73, v78, v79
	v_add_f32_e32 v72, v72, v73
	v_add_f32_e32 v73, v82, v83
	v_add_f32_e32 v74, v80, v81
	v_add_f32_e32 v73, v73, v74
	v_add_f32_e32 v72, v72, v73
	v_add_f32_e32 v86, 0, v72
	v_mul_f32_e32 v72, v77, v77
	v_mul_f32_e32 v73, v79, v79
	v_fmac_f32_e32 v72, v76, v76
	v_fmac_f32_e32 v73, v78, v78
	v_add_f32_e32 v72, v72, v73
	v_mul_f32_e32 v73, v83, v83
	v_mul_f32_e32 v74, v81, v81
	v_fmac_f32_e32 v73, v82, v82
	v_fmac_f32_e32 v74, v80, v80
	v_add_f32_e32 v73, v73, v74
	v_add_f32_e32 v80, v72, v73
	v_lshlrev_b32_e32 v72, 16, v128
	v_and_b32_e32 v73, 0xffff0000, v128
	v_lshlrev_b32_e32 v74, 16, v129
	v_and_b32_e32 v75, 0xffff0000, v129
	v_lshlrev_b32_e32 v76, 16, v130
	v_and_b32_e32 v77, 0xffff0000, v130
	v_lshlrev_b32_e32 v78, 16, v131
	v_and_b32_e32 v79, 0xffff0000, v131
	v_pk_fma_f32 v[70:71], v[74:75], s[28:29], v[70:71] op_sel_hi:[1,0,1]
	v_pk_fma_f32 v[68:69], v[72:73], s[28:29], v[68:69] op_sel_hi:[1,0,1]
	v_pk_fma_f32 v[74:75], v[76:77], s[28:29], v[64:65] op_sel_hi:[1,0,1]
	v_cvt_pk_bf16_f32 v64, v68, v69
	v_cvt_pk_bf16_f32 v65, v70, v71
	v_pk_fma_f32 v[72:73], v[78:79], s[28:29], v[66:67] op_sel_hi:[1,0,1]
	v_cvt_pk_bf16_f32 v66, v74, v75
	s_nop 0
	v_cvt_pk_bf16_f32 v67, v72, v73
	global_store_dwordx4 v[84:85], v[64:67], off offset:256
	s_nop 1
	v_add_f32_e32 v64, v68, v69
	v_add_f32_e32 v65, v70, v71
	v_add_f32_e32 v64, v64, v65
	v_add_f32_e32 v65, v74, v75
	v_add_f32_e32 v66, v72, v73
	v_add_f32_e32 v65, v65, v66
	v_add_f32_e32 v64, v64, v65
	v_mul_f32_e32 v65, v69, v69
	v_mul_f32_e32 v66, v71, v71
	v_fmac_f32_e32 v65, v68, v68
	v_fmac_f32_e32 v66, v70, v70
	v_add_f32_e32 v65, v65, v66
	v_mul_f32_e32 v66, v75, v75
	v_mul_f32_e32 v67, v73, v73
	v_fmac_f32_e32 v66, v74, v74
	v_fmac_f32_e32 v67, v72, v72
	v_add_f32_e32 v66, v66, v67
	v_add_f32_e32 v65, v65, v66
	v_add_f32_e32 v64, v86, v64
	v_add_f32_e32 v66, v80, v65
	v_mov_b32_e32 v65, v64
	v_mov_b32_e32 v67, v66
	s_nop 0
	v_permlane16_swap_b32_e32 v64, v65
	v_permlane16_swap_b32_e32 v66, v67
	v_add_f32_e32 v64, v64, v65
	v_add_f32_e32 v66, v66, v67
	v_mov_b32_e32 v65, v64
	v_mov_b32_e32 v67, v66
	s_nop 0
	v_permlane32_swap_b32_e32 v64, v65
	v_permlane32_swap_b32_e32 v66, v67
	s_and_saveexec_b64 s[12:13], s[42:43]
	s_cbranch_execz .LBB0_1115
	v_add_f32_e32 v64, v64, v65
	v_mul_f32_e32 v64, 0x46800000, v64
	v_add_f32_e32 v66, v66, v67
	v_rndne_f32_e32 v64, v64
	v_cvt_i32_f32_e32 v65, v64
	v_mul_f32_e32 v64, 0x44800000, v66
	v_rndne_f32_e32 v64, v64
	v_cvt_u32_f32_e32 v64, v64
	global_atomic_add_x2 v[112:113], v[64:65], off offset:384
; __device__ __forceinline__ u32x4 pack8(f32x4 a, f32x4 b) { u32x4 w; w.x = cvt_pk_bf16(a[0], a[1]); w.y = cvt_pk_bf16(a[2], a[3]); w.z = cvt_pk_bf16(b[0], b[1]); w.w = cvt_pk_bf16(b[2], b[3]); return w; }
; __device__ __forceinline__ float bf_lo(unsigned w) { return __uint_as_float(w << 16); }
; __device__ __forceinline__ float bf_hi(unsigned w) { return __uint_as_float(w & 0xffff0000u); }
; __device__ __forceinline__ float hsum4(f32x4 v) { return (v[0] + v[1]) + (v[2] + v[3]); }
; __device__ __forceinline__ float hsq4(f32x4 v) { return (v[0] * v[0] + v[1] * v[1]) + (v[2] * v[2] + v[3] * v[3]); }
; __device__ __forceinline__ float fq_sum(float s) { return x16x32_sum(s); }
;     __device__ __forceinline__ void operator()(EP_ARGS) const {
;     ...
;                     for (int bj = 0; bj < 2; ++bj) rw[m][bj] = *(const u32x4*)(xh + (size_t)EP_ROW(ai, m) * DM + EP_COL8(bj));
;                 __builtin_amdgcn_sched_barrier(0); }
; #pragma unroll
;             for (int m = 0; m < 4; ++m) { const int row = EP_ROW(ai, m); float s = 0.f, q = 0.f;
; #pragma unroll
;                 for (int bj = 0; bj < 2; ++bj) { const size_t o = (size_t)row * DM + EP_COL8(bj);
;                     f32x4 r0, r1; if (xf) { r0 = *(const f32x4*)(xf + o); r1 = *(const f32x4*)(xf + o + 4); }
;                     else { const u32x4 w = rw[m][bj]; r0 = (f32x4){bf_lo(w.x), bf_hi(w.x), bf_lo(w.y), bf_hi(w.y)}; r1 = (f32x4){bf_lo(w.z), bf_hi(w.z), bf_lo(w.w), bf_hi(w.w)}; }
;                     const f32x4 y0 = r0 * ALPHA + acc[ai][bj][m][0], y1 = r1 * ALPHA + acc[ai][bj][m][1];
;                     *(u32x4*)(Yh + o) = pack8(y0, y1);
;                     s += hsum4(y0) + hsum4(y1); q += hsq4(y0) + hsq4(y1); }
;                 s = fq_sum(s); q = fq_sum(q);
;                 if (fq == 0) atomic_add_stat(stats + (size_t)row, s, q); }
.LBB0_1115:
	s_or_b64 exec, exec, s[12:13]
	v_add_u32_e32 v64, 0x80, v156
	v_ashrrev_i32_e32 v65, 31, v64
	v_lshlrev_b64 v[102:103], 12, v[64:65]
	v_lshl_add_u64 v[64:65], s[4:5], 0, v[102:103]
	v_lshl_add_u64 v[64:65], v[64:65], 0, v[154:155]
	v_add_u32_e32 v64, 0x90, v156
	v_ashrrev_i32_e32 v65, 31, v64
	v_lshlrev_b64 v[92:93], 12, v[64:65]
	v_lshl_add_u64 v[64:65], s[4:5], 0, v[92:93]
	v_lshl_add_u64 v[64:65], v[64:65], 0, v[154:155]
	v_add_u32_e32 v64, 0xa0, v156
	v_ashrrev_i32_e32 v65, 31, v64
	v_lshlrev_b64 v[90:91], 12, v[64:65]
	v_lshl_add_u64 v[64:65], s[4:5], 0, v[90:91]
	v_lshl_add_u64 v[64:65], v[64:65], 0, v[154:155]
	v_add_u32_e32 v64, 0xb0, v156
	v_ashrrev_i32_e32 v65, 31, v64
	v_lshlrev_b64 v[88:89], 12, v[64:65]
	v_lshl_add_u64 v[64:65], s[4:5], 0, v[88:89]
	v_lshl_add_u64 v[64:65], v[64:65], 0, v[154:155]
	s_nop 0
	s_waitcnt vmcnt(8)
	v_lshlrev_b32_e32 v104, 16, v194
	v_and_b32_e32 v105, 0xffff0000, v194
	v_lshlrev_b32_e32 v94, 16, v195
	v_and_b32_e32 v95, 0xffff0000, v195
	v_lshlrev_b32_e32 v106, 16, v196
	v_and_b32_e32 v107, 0xffff0000, v196
	v_lshlrev_b32_e32 v96, 16, v197
	v_and_b32_e32 v97, 0xffff0000, v197
	v_lshl_add_u64 v[102:103], s[6:7], 0, v[102:103]
	v_pk_fma_f32 v[62:63], v[94:95], s[28:29], v[62:63] op_sel_hi:[1, 0, 1]
	v_pk_fma_f32 v[60:61], v[104:105], s[28:29], v[60:61] op_sel_hi:[1, 0, 1]
	v_pk_fma_f32 v[94:95], v[96:97], s[28:29], v[58:59] op_sel_hi:[1, 0, 1]
	v_pk_fma_f32 v[96:97], v[106:107], s[28:29], v[56:57] op_sel_hi:[1, 0, 1]
	v_cvt_pk_bf16_f32 v56, v60, v61
	v_cvt_pk_bf16_f32 v57, v62, v63
	v_lshl_add_u64 v[102:103], v[102:103], 0, v[154:155]
	v_cvt_pk_bf16_f32 v58, v96, v97
	v_cvt_pk_bf16_f32 v59, v94, v95
	global_store_dwordx4 v[102:103], v[56:59], off
	s_nop 1
	v_add_f32_e32 v56, v60, v61
	v_add_f32_e32 v57, v62, v63
	v_add_f32_e32 v56, v56, v57
	v_add_f32_e32 v57, v96, v97
	v_add_f32_e32 v58, v94, v95
	v_add_f32_e32 v57, v57, v58
	v_add_f32_e32 v56, v56, v57
	v_add_f32_e32 v104, 0, v56
	v_mul_f32_e32 v56, v61, v61
	v_mul_f32_e32 v57, v63, v63
	v_fmac_f32_e32 v56, v60, v60
	v_fmac_f32_e32 v57, v62, v62
	v_add_f32_e32 v56, v56, v57
	v_mul_f32_e32 v57, v97, v97
	v_mul_f32_e32 v58, v95, v95
	v_fmac_f32_e32 v57, v96, v96
	v_fmac_f32_e32 v58, v94, v94
	v_add_f32_e32 v57, v57, v58
	v_add_f32_e32 v94, v56, v57
	v_lshlrev_b32_e32 v56, 16, v198
	v_and_b32_e32 v57, 0xffff0000, v198
	v_lshlrev_b32_e32 v58, 16, v199
	v_and_b32_e32 v59, 0xffff0000, v199
	v_lshlrev_b32_e32 v60, 16, v200
	v_and_b32_e32 v61, 0xffff0000, v200
	v_lshlrev_b32_e32 v62, 16, v201
	v_and_b32_e32 v63, 0xffff0000, v201
	v_pk_fma_f32 v[54:55], v[58:59], s[28:29], v[54:55] op_sel_hi:[1, 0, 1]
	v_pk_fma_f32 v[52:53], v[56:57], s[28:29], v[52:53] op_sel_hi:[1, 0, 1]
	v_pk_fma_f32 v[58:59], v[60:61], s[28:29], v[48:49] op_sel_hi:[1, 0, 1]
	v_cvt_pk_bf16_f32 v48, v52, v53
	v_cvt_pk_bf16_f32 v49, v54, v55
	v_pk_fma_f32 v[56:57], v[62:63], s[28:29], v[50:51] op_sel_hi:[1, 0, 1]
	v_cvt_pk_bf16_f32 v50, v58, v59
	s_nop 0
	v_cvt_pk_bf16_f32 v51, v56, v57
	global_store_dwordx4 v[102:103], v[48:51], off offset:256
	s_nop 1
	v_add_f32_e32 v48, v52, v53
	v_add_f32_e32 v49, v54, v55
	v_add_f32_e32 v48, v48, v49
	v_add_f32_e32 v49, v58, v59
	v_add_f32_e32 v50, v56, v57
	v_add_f32_e32 v49, v49, v50
	v_add_f32_e32 v48, v48, v49
	v_mul_f32_e32 v49, v53, v53
	v_mul_f32_e32 v50, v55, v55
	v_fmac_f32_e32 v49, v52, v52
	v_fmac_f32_e32 v50, v54, v54
	v_add_f32_e32 v49, v49, v50
	v_mul_f32_e32 v50, v59, v59
	v_mul_f32_e32 v51, v57, v57
	v_fmac_f32_e32 v50, v58, v58
	v_fmac_f32_e32 v51, v56, v56
	v_add_f32_e32 v50, v50, v51
	v_add_f32_e32 v49, v49, v50
	v_add_f32_e32 v48, v104, v48
	v_add_f32_e32 v50, v94, v49
	v_mov_b32_e32 v49, v48
	v_mov_b32_e32 v51, v50
	s_nop 0
	v_permlane16_swap_b32_e32 v48, v49
	v_permlane16_swap_b32_e32 v50, v51
	v_add_f32_e32 v48, v48, v49
	v_add_f32_e32 v50, v50, v51
	v_mov_b32_e32 v49, v48
	v_mov_b32_e32 v51, v50
	s_nop 0
	v_permlane32_swap_b32_e32 v48, v49
	v_permlane32_swap_b32_e32 v50, v51
	s_and_saveexec_b64 s[12:13], s[42:43]
	s_cbranch_execz .LBB0_1117
	v_add_f32_e32 v48, v48, v49
	v_mul_f32_e32 v48, 0x46800000, v48
	v_add_f32_e32 v50, v50, v51
	v_rndne_f32_e32 v48, v48
	v_cvt_i32_f32_e32 v49, v48
	v_mul_f32_e32 v48, 0x44800000, v50
	v_rndne_f32_e32 v48, v48
	v_cvt_u32_f32_e32 v48, v48
	global_atomic_add_x2 v[112:113], v[48:49], off offset:1024
; __device__ __forceinline__ u32x4 pack8(f32x4 a, f32x4 b) { u32x4 w; w.x = cvt_pk_bf16(a[0], a[1]); w.y = cvt_pk_bf16(a[2], a[3]); w.z = cvt_pk_bf16(b[0], b[1]); w.w = cvt_pk_bf16(b[2], b[3]); return w; }
; __device__ __forceinline__ float bf_lo(unsigned w) { return __uint_as_float(w << 16); }
; __device__ __forceinline__ float bf_hi(unsigned w) { return __uint_as_float(w & 0xffff0000u); }
; __device__ __forceinline__ float hsum4(f32x4 v) { return (v[0] + v[1]) + (v[2] + v[3]); }
; __device__ __forceinline__ float hsq4(f32x4 v) { return (v[0] * v[0] + v[1] * v[1]) + (v[2] * v[2] + v[3] * v[3]); }
; __device__ __forceinline__ float fq_sum(float s) { return x16x32_sum(s); }
;     __device__ __forceinline__ void operator()(EP_ARGS) const {
;     ...
;             for (int m = 0; m < 4; ++m) { const int row = EP_ROW(ai, m); float s = 0.f, q = 0.f;
; #pragma unroll
;                 for (int bj = 0; bj < 2; ++bj) { const size_t o = (size_t)row * DM + EP_COL8(bj);
;                     f32x4 r0, r1; if (xf) { r0 = *(const f32x4*)(xf + o); r1 = *(const f32x4*)(xf + o + 4); }
;                     else { const u32x4 w = rw[m][bj]; r0 = (f32x4){bf_lo(w.x), bf_hi(w.x), bf_lo(w.y), bf_hi(w.y)}; r1 = (f32x4){bf_lo(w.z), bf_hi(w.z), bf_lo(w.w), bf_hi(w.w)}; }
;                     const f32x4 y0 = r0 * ALPHA + acc[ai][bj][m][0], y1 = r1 * ALPHA + acc[ai][bj][m][1];
;                     *(u32x4*)(Yh + o) = pack8(y0, y1);
;                     s += hsum4(y0) + hsum4(y1); q += hsq4(y0) + hsq4(y1); }
;                 s = fq_sum(s); q = fq_sum(q);
;                 if (fq == 0) atomic_add_stat(stats + (size_t)row, s, q); }
.LBB0_1117:
	s_or_b64 exec, exec, s[12:13]
	v_lshlrev_b32_e32 v50, 16, v203
	v_and_b32_e32 v51, 0xffff0000, v203
	v_lshlrev_b32_e32 v52, 16, v204
	v_and_b32_e32 v53, 0xffff0000, v204
	v_lshlrev_b32_e32 v48, 16, v202
	v_and_b32_e32 v49, 0xffff0000, v202
	v_pk_fma_f32 v[46:47], v[50:51], s[28:29], v[46:47] op_sel_hi:[1, 0, 1]
	v_pk_fma_f32 v[50:51], v[52:53], s[28:29], v[40:41] op_sel_hi:[1, 0, 1]
	v_lshl_add_u64 v[52:53], s[6:7], 0, v[92:93]
	v_lshlrev_b32_e32 v54, 16, v205
	v_and_b32_e32 v55, 0xffff0000, v205
	v_pk_fma_f32 v[44:45], v[48:49], s[28:29], v[44:45] op_sel_hi:[1, 0, 1]
	v_lshl_add_u64 v[52:53], v[152:153], 1, v[52:53]
	v_cvt_pk_bf16_f32 v40, v44, v45
	v_cvt_pk_bf16_f32 v41, v46, v47
	v_pk_fma_f32 v[48:49], v[54:55], s[28:29], v[42:43] op_sel_hi:[1, 0, 1]
	v_cvt_pk_bf16_f32 v42, v50, v51
	s_nop 0
	v_cvt_pk_bf16_f32 v43, v48, v49
	global_store_dwordx4 v[52:53], v[40:43], off
	s_nop 1
	v_add_f32_e32 v40, v44, v45
	v_add_f32_e32 v41, v46, v47
	v_add_f32_e32 v40, v40, v41
	v_add_f32_e32 v41, v50, v51
	v_add_f32_e32 v42, v48, v49
	v_add_f32_e32 v41, v41, v42
	v_add_f32_e32 v40, v40, v41
	v_add_f32_e32 v54, 0, v40
	v_mul_f32_e32 v40, v45, v45
	v_mul_f32_e32 v41, v47, v47
	v_fmac_f32_e32 v40, v44, v44
	v_fmac_f32_e32 v41, v46, v46
	v_add_f32_e32 v40, v40, v41
	v_mul_f32_e32 v41, v51, v51
	v_mul_f32_e32 v42, v49, v49
	v_fmac_f32_e32 v41, v50, v50
	v_fmac_f32_e32 v42, v48, v48
	v_add_f32_e32 v41, v41, v42
	v_add_f32_e32 v48, v40, v41
	v_lshlrev_b32_e32 v40, 16, v206
	v_and_b32_e32 v41, 0xffff0000, v206
	v_lshlrev_b32_e32 v42, 16, v207
	v_and_b32_e32 v43, 0xffff0000, v207
	v_lshlrev_b32_e32 v44, 16, v208
	v_and_b32_e32 v45, 0xffff0000, v208
	v_lshlrev_b32_e32 v46, 16, v209
	v_and_b32_e32 v47, 0xffff0000, v209
	v_pk_fma_f32 v[38:39], v[42:43], s[28:29], v[38:39] op_sel_hi:[1, 0, 1]
	v_pk_fma_f32 v[36:37], v[40:41], s[28:29], v[36:37] op_sel_hi:[1, 0, 1]
	v_pk_fma_f32 v[42:43], v[44:45], s[28:29], v[32:33] op_sel_hi:[1, 0, 1]
	v_cvt_pk_bf16_f32 v32, v36, v37
	v_cvt_pk_bf16_f32 v33, v38, v39
	v_pk_fma_f32 v[40:41], v[46:47], s[28:29], v[34:35] op_sel_hi:[1, 0, 1]
	v_cvt_pk_bf16_f32 v34, v42, v43
	s_nop 0
	v_cvt_pk_bf16_f32 v35, v40, v41
	global_store_dwordx4 v[52:53], v[32:35], off offset:256
	s_nop 1
	v_add_f32_e32 v32, v36, v37
	v_add_f32_e32 v33, v38, v39
	v_add_f32_e32 v32, v32, v33
	v_add_f32_e32 v33, v42, v43
	v_add_f32_e32 v34, v40, v41
	v_add_f32_e32 v33, v33, v34
	v_add_f32_e32 v32, v32, v33
	v_mul_f32_e32 v33, v37, v37
	v_mul_f32_e32 v34, v39, v39
	v_fmac_f32_e32 v33, v36, v36
	v_fmac_f32_e32 v34, v38, v38
	v_add_f32_e32 v33, v33, v34
	v_mul_f32_e32 v34, v43, v43
	v_mul_f32_e32 v35, v41, v41
	v_fmac_f32_e32 v34, v42, v42
	v_fmac_f32_e32 v35, v40, v40
	v_add_f32_e32 v34, v34, v35
	v_add_f32_e32 v33, v33, v34
	v_add_f32_e32 v32, v54, v32
	v_add_f32_e32 v34, v48, v33
	v_mov_b32_e32 v33, v32
	v_mov_b32_e32 v35, v34
	s_nop 0
	v_permlane16_swap_b32_e32 v32, v33
	v_permlane16_swap_b32_e32 v34, v35
	v_add_f32_e32 v32, v32, v33
	v_add_f32_e32 v34, v34, v35
	v_mov_b32_e32 v33, v32
	v_mov_b32_e32 v35, v34
	s_nop 0
	v_permlane32_swap_b32_e32 v32, v33
	v_permlane32_swap_b32_e32 v34, v35
	s_and_saveexec_b64 s[12:13], s[42:43]
	s_cbranch_execz .LBB0_1119
	v_add_f32_e32 v32, v32, v33
	v_mul_f32_e32 v32, 0x46800000, v32
	v_add_f32_e32 v34, v34, v35
	v_rndne_f32_e32 v32, v32
	v_cvt_i32_f32_e32 v33, v32
	v_mul_f32_e32 v32, 0x44800000, v34
	v_rndne_f32_e32 v32, v32
	v_cvt_u32_f32_e32 v32, v32
	global_atomic_add_x2 v[112:113], v[32:33], off offset:1152
; __device__ __forceinline__ u32x4 pack8(f32x4 a, f32x4 b) { u32x4 w; w.x = cvt_pk_bf16(a[0], a[1]); w.y = cvt_pk_bf16(a[2], a[3]); w.z = cvt_pk_bf16(b[0], b[1]); w.w = cvt_pk_bf16(b[2], b[3]); return w; }
; __device__ __forceinline__ float bf_lo(unsigned w) { return __uint_as_float(w << 16); }
; __device__ __forceinline__ float bf_hi(unsigned w) { return __uint_as_float(w & 0xffff0000u); }
; __device__ __forceinline__ float hsum4(f32x4 v) { return (v[0] + v[1]) + (v[2] + v[3]); }
; __device__ __forceinline__ float hsq4(f32x4 v) { return (v[0] * v[0] + v[1] * v[1]) + (v[2] * v[2] + v[3] * v[3]); }
; __device__ __forceinline__ float fq_sum(float s) { return x16x32_sum(s); }
;     __device__ __forceinline__ void operator()(EP_ARGS) const {
;     ...
;             for (int m = 0; m < 4; ++m) { const int row = EP_ROW(ai, m); float s = 0.f, q = 0.f;
; #pragma unroll
;                 for (int bj = 0; bj < 2; ++bj) { const size_t o = (size_t)row * DM + EP_COL8(bj);
;                     f32x4 r0, r1; if (xf) { r0 = *(const f32x4*)(xf + o); r1 = *(const f32x4*)(xf + o + 4); }
;                     else { const u32x4 w = rw[m][bj]; r0 = (f32x4){bf_lo(w.x), bf_hi(w.x), bf_lo(w.y), bf_hi(w.y)}; r1 = (f32x4){bf_lo(w.z), bf_hi(w.z), bf_lo(w.w), bf_hi(w.w)}; }
;                     const f32x4 y0 = r0 * ALPHA + acc[ai][bj][m][0], y1 = r1 * ALPHA + acc[ai][bj][m][1];
;                     *(u32x4*)(Yh + o) = pack8(y0, y1);
;                     s += hsum4(y0) + hsum4(y1); q += hsq4(y0) + hsq4(y1); }
;                 s = fq_sum(s); q = fq_sum(q);
;                 if (fq == 0) atomic_add_stat(stats + (size_t)row, s, q); }
.LBB0_1119:
	s_or_b64 exec, exec, s[12:13]
	v_lshlrev_b32_e32 v34, 16, v215
	v_and_b32_e32 v35, 0xffff0000, v215
	v_lshlrev_b32_e32 v36, 16, v216
	v_and_b32_e32 v37, 0xffff0000, v216
	v_lshlrev_b32_e32 v32, 16, v214
	v_and_b32_e32 v33, 0xffff0000, v214
	v_pk_fma_f32 v[30:31], v[34:35], s[28:29], v[30:31] op_sel_hi:[1, 0, 1]
	v_pk_fma_f32 v[34:35], v[36:37], s[28:29], v[24:25] op_sel_hi:[1, 0, 1]
	v_lshl_add_u64 v[36:37], s[6:7], 0, v[90:91]
	v_lshlrev_b32_e32 v38, 16, v217
	v_and_b32_e32 v39, 0xffff0000, v217
	v_pk_fma_f32 v[28:29], v[32:33], s[28:29], v[28:29] op_sel_hi:[1, 0, 1]
	v_lshl_add_u64 v[36:37], v[152:153], 1, v[36:37]
	v_cvt_pk_bf16_f32 v24, v28, v29
	v_cvt_pk_bf16_f32 v25, v30, v31
	v_pk_fma_f32 v[32:33], v[38:39], s[28:29], v[26:27] op_sel_hi:[1, 0, 1]
	v_cvt_pk_bf16_f32 v26, v34, v35
	s_nop 0
	v_cvt_pk_bf16_f32 v27, v32, v33
	global_store_dwordx4 v[36:37], v[24:27], off
	s_nop 1
	v_add_f32_e32 v24, v28, v29
	v_add_f32_e32 v25, v30, v31
	v_add_f32_e32 v24, v24, v25
	v_add_f32_e32 v25, v34, v35
	v_add_f32_e32 v26, v32, v33
	v_add_f32_e32 v25, v25, v26
	v_add_f32_e32 v24, v24, v25
	v_add_f32_e32 v38, 0, v24
	v_mul_f32_e32 v24, v29, v29
	v_mul_f32_e32 v25, v31, v31
	v_fmac_f32_e32 v24, v28, v28
	v_fmac_f32_e32 v25, v30, v30
	v_add_f32_e32 v24, v24, v25
	v_mul_f32_e32 v25, v35, v35
	v_mul_f32_e32 v26, v33, v33
	v_fmac_f32_e32 v25, v34, v34
	v_fmac_f32_e32 v26, v32, v32
	v_add_f32_e32 v25, v25, v26
	v_add_f32_e32 v32, v24, v25
	v_lshlrev_b32_e32 v24, 16, v232
	v_and_b32_e32 v25, 0xffff0000, v232
	v_lshlrev_b32_e32 v26, 16, v233
	v_and_b32_e32 v27, 0xffff0000, v233
	v_lshlrev_b32_e32 v28, 16, v234
	v_and_b32_e32 v29, 0xffff0000, v234
	v_lshlrev_b32_e32 v30, 16, v235
	v_and_b32_e32 v31, 0xffff0000, v235
	v_pk_fma_f32 v[22:23], v[26:27], s[28:29], v[22:23] op_sel_hi:[1, 0, 1]
	v_pk_fma_f32 v[20:21], v[24:25], s[28:29], v[20:21] op_sel_hi:[1, 0, 1]
	v_pk_fma_f32 v[26:27], v[28:29], s[28:29], v[16:17] op_sel_hi:[1, 0, 1]
	v_cvt_pk_bf16_f32 v16, v20, v21
	v_cvt_pk_bf16_f32 v17, v22, v23
	v_pk_fma_f32 v[24:25], v[30:31], s[28:29], v[18:19] op_sel_hi:[1, 0, 1]
	v_cvt_pk_bf16_f32 v18, v26, v27
	s_nop 0
	v_cvt_pk_bf16_f32 v19, v24, v25
	global_store_dwordx4 v[36:37], v[16:19], off offset:256
	s_nop 1
	v_add_f32_e32 v16, v20, v21
	v_add_f32_e32 v17, v22, v23
	v_add_f32_e32 v16, v16, v17
	v_add_f32_e32 v17, v26, v27
	v_add_f32_e32 v18, v24, v25
	v_add_f32_e32 v17, v17, v18
	v_add_f32_e32 v16, v16, v17
	v_mul_f32_e32 v17, v21, v21
	v_mul_f32_e32 v18, v23, v23
	v_fmac_f32_e32 v17, v20, v20
	v_fmac_f32_e32 v18, v22, v22
	v_add_f32_e32 v17, v17, v18
	v_mul_f32_e32 v18, v27, v27
	v_mul_f32_e32 v19, v25, v25
	v_fmac_f32_e32 v18, v26, v26
	v_fmac_f32_e32 v19, v24, v24
	v_add_f32_e32 v18, v18, v19
	v_add_f32_e32 v17, v17, v18
	v_add_f32_e32 v16, v38, v16
	v_add_f32_e32 v18, v32, v17
	v_mov_b32_e32 v17, v16
	v_mov_b32_e32 v19, v18
	s_nop 0
	v_permlane16_swap_b32_e32 v16, v17
	v_permlane16_swap_b32_e32 v18, v19
	v_add_f32_e32 v16, v16, v17
	v_add_f32_e32 v18, v18, v19
	v_mov_b32_e32 v17, v16
	v_mov_b32_e32 v19, v18
	s_nop 0
	v_permlane32_swap_b32_e32 v16, v17
	v_permlane32_swap_b32_e32 v18, v19
	s_and_saveexec_b64 s[12:13], s[42:43]
	s_cbranch_execz .LBB0_1121
	v_add_f32_e32 v16, v16, v17
	v_mul_f32_e32 v16, 0x46800000, v16
	v_add_f32_e32 v18, v18, v19
	v_rndne_f32_e32 v16, v16
	v_cvt_i32_f32_e32 v17, v16
	v_mul_f32_e32 v16, 0x44800000, v18
	v_rndne_f32_e32 v16, v16
	v_cvt_u32_f32_e32 v16, v16
	global_atomic_add_x2 v[112:113], v[16:17], off offset:1280
.LBB0_1121:
	s_or_b64 exec, exec, s[12:13]
	v_lshlrev_b32_e32 v18, 16, v237
	v_and_b32_e32 v19, 0xffff0000, v237
	v_lshlrev_b32_e32 v20, 16, v238
	v_and_b32_e32 v21, 0xffff0000, v238
	v_lshlrev_b32_e32 v16, 16, v236
	v_and_b32_e32 v17, 0xffff0000, v236
	v_pk_fma_f32 v[14:15], v[18:19], s[28:29], v[14:15] op_sel_hi:[1, 0, 1]
	v_pk_fma_f32 v[18:19], v[20:21], s[28:29], v[8:9] op_sel_hi:[1, 0, 1]
	v_lshl_add_u64 v[20:21], s[6:7], 0, v[88:89]
	v_lshlrev_b32_e32 v22, 16, v239
	v_and_b32_e32 v23, 0xffff0000, v239
	v_pk_fma_f32 v[12:13], v[16:17], s[28:29], v[12:13] op_sel_hi:[1, 0, 1]
	v_lshl_add_u64 v[20:21], v[152:153], 1, v[20:21]
	v_cvt_pk_bf16_f32 v8, v12, v13
	v_cvt_pk_bf16_f32 v9, v14, v15
	v_pk_fma_f32 v[16:17], v[22:23], s[28:29], v[10:11] op_sel_hi:[1, 0, 1]
	v_cvt_pk_bf16_f32 v10, v18, v19
	s_nop 0
	v_cvt_pk_bf16_f32 v11, v16, v17
	global_store_dwordx4 v[20:21], v[8:11], off
	s_nop 1
	v_add_f32_e32 v8, v12, v13
	v_add_f32_e32 v9, v14, v15
	v_add_f32_e32 v8, v8, v9
	v_add_f32_e32 v9, v18, v19
	v_add_f32_e32 v10, v16, v17
	v_add_f32_e32 v9, v9, v10
	v_add_f32_e32 v8, v8, v9
	v_add_f32_e32 v22, 0, v8
	v_mul_f32_e32 v8, v13, v13
	v_mul_f32_e32 v9, v15, v15
	v_fmac_f32_e32 v8, v12, v12
	v_fmac_f32_e32 v9, v14, v14
	v_add_f32_e32 v8, v8, v9
	v_mul_f32_e32 v9, v19, v19
	v_mul_f32_e32 v10, v17, v17
	v_fmac_f32_e32 v9, v18, v18
	v_fmac_f32_e32 v10, v16, v16
	v_add_f32_e32 v9, v9, v10
	v_add_f32_e32 v16, v8, v9
	v_lshlrev_b32_e32 v8, 16, v240
	v_and_b32_e32 v9, 0xffff0000, v240
	v_lshlrev_b32_e32 v10, 16, v241
	v_and_b32_e32 v11, 0xffff0000, v241
	v_lshlrev_b32_e32 v12, 16, v242
	v_and_b32_e32 v13, 0xffff0000, v242
	v_lshlrev_b32_e32 v14, 16, v243
	v_and_b32_e32 v15, 0xffff0000, v243
	v_pk_fma_f32 v[6:7], v[10:11], s[28:29], v[6:7] op_sel_hi:[1, 0, 1]
	v_pk_fma_f32 v[4:5], v[8:9], s[28:29], v[4:5] op_sel_hi:[1, 0, 1]
	v_pk_fma_f32 v[10:11], v[12:13], s[28:29], v[0:1] op_sel_hi:[1, 0, 1]
	v_cvt_pk_bf16_f32 v0, v4, v5
	v_cvt_pk_bf16_f32 v1, v6, v7
	v_pk_fma_f32 v[8:9], v[14:15], s[28:29], v[2:3] op_sel_hi:[1, 0, 1]
	v_cvt_pk_bf16_f32 v2, v10, v11
	s_nop 0
	v_cvt_pk_bf16_f32 v3, v8, v9
	global_store_dwordx4 v[20:21], v[0:3], off offset:256
	s_nop 1
	v_add_f32_e32 v0, v4, v5
	v_add_f32_e32 v1, v6, v7
	v_add_f32_e32 v0, v0, v1
	v_add_f32_e32 v1, v10, v11
	v_add_f32_e32 v2, v8, v9
	v_add_f32_e32 v1, v1, v2
	v_add_f32_e32 v0, v0, v1
	v_mul_f32_e32 v1, v5, v5
	v_mul_f32_e32 v2, v7, v7
	v_fmac_f32_e32 v1, v4, v4
	v_fmac_f32_e32 v2, v6, v6
	v_add_f32_e32 v1, v1, v2
	v_mul_f32_e32 v2, v11, v11
	v_mul_f32_e32 v3, v9, v9
	v_fmac_f32_e32 v2, v10, v10
	v_fmac_f32_e32 v3, v8, v8
	v_add_f32_e32 v2, v2, v3
	v_add_f32_e32 v1, v1, v2
	v_add_f32_e32 v0, v22, v0
	v_add_f32_e32 v2, v16, v1
	v_mov_b32_e32 v1, v0
	v_mov_b32_e32 v3, v2
	s_nop 0
	v_permlane16_swap_b32_e32 v0, v1
	v_permlane16_swap_b32_e32 v2, v3
	v_add_f32_e32 v0, v0, v1
	v_add_f32_e32 v2, v2, v3
	v_mov_b32_e32 v1, v0
	v_mov_b32_e32 v3, v2
	s_nop 0
	v_permlane32_swap_b32_e32 v0, v1
	v_permlane32_swap_b32_e32 v2, v3
	s_and_saveexec_b64 s[12:13], s[42:43]
	s_cbranch_execz .LBB0_1123
	v_add_f32_e32 v0, v0, v1
	v_mul_f32_e32 v0, 0x46800000, v0
	v_add_f32_e32 v2, v2, v3
	v_rndne_f32_e32 v0, v0
	v_cvt_i32_f32_e32 v1, v0
	v_mul_f32_e32 v0, 0x44800000, v2
	v_rndne_f32_e32 v0, v0
	v_cvt_u32_f32_e32 v0, v0
	global_atomic_add_x2 v[112:113], v[0:1], off offset:1408
